# GEMM K loop: M0 written one MFMA ahead of each LDS-DMA (MFMA is the wait state), 8 s_nop per iteration dropped
# speedup vs baseline: 1.0088x; 1.0088x over previous
.LBB0_246:
	s_add_i32 s10, s7, 0xffffa000
	s_cmp_lg_u32 s7, 0
	s_cselect_b32 s12, s10, 0xc000
	v_add_u32_e32 v131, s7, v150
	s_waitcnt vmcnt(6)
	s_barrier
	v_add_u32_e32 v133, s7, v149
	ds_read_b128 v[154:157], v131 offset:0
	ds_read_b128 v[158:161], v131 offset:0x400
	ds_read_b128 v[162:165], v131 offset:0x800
	ds_read_b128 v[166:169], v131 offset:0xc00
	v_add_u32_e32 v131, s12, v147
	ds_read_b128 v[170:173], v133 offset:0
	ds_read_b128 v[174:177], v133 offset:0x400
	ds_read_b128 v[178:181], v133 offset:0x800
	ds_read_b128 v[200:203], v133 offset:0xc00
	s_add_u32 s10, s8, s50
	s_addc_u32 s11, s9, s51
	v_readfirstlane_b32 s13, v131
	s_add_u32 s64, s5, s100
	s_addc_u32 s65, s6, 0
	s_sub_i32 s68, s13, s12
	s_lshr_b32 s68, s68, 1
	s_add_i32 s68, s68, s12
	s_addk_i32 s68, 0x4000
	s_waitcnt lgkmcnt(0)
	v_mfma_f32_16x16x32_bf16 v[126:129], v[154:157], v[170:173], v[126:129]
	ds_read_b128 v[204:207], v133 offset:0x1000
	v_mfma_f32_16x16x32_bf16 v[122:125], v[154:157], v[174:177], v[122:125]
	ds_read_b128 v[208:211], v133 offset:0x1400
	v_mfma_f32_16x16x32_bf16 v[118:121], v[154:157], v[178:181], v[118:121]
	ds_read_b128 v[212:215], v133 offset:0x1800
	v_mfma_f32_16x16x32_bf16 v[114:117], v[154:157], v[200:203], v[114:117]
	ds_read_b128 v[216:219], v133 offset:0x1c00
	s_mov_b32 m0, s13
	v_mfma_f32_16x16x32_bf16 v[110:113], v[158:161], v[170:173], v[110:113]
	global_load_lds_dwordx4 v0, s[10:11]
	v_mfma_f32_16x16x32_bf16 v[102:105], v[158:161], v[174:177], v[102:105]
	v_mfma_f32_16x16x32_bf16 v[94:97], v[158:161], v[178:181], v[94:97]
	s_add_u32 m0, s13, 0x400
	v_mfma_f32_16x16x32_bf16 v[86:89], v[158:161], v[200:203], v[86:89]
	global_load_lds_dwordx4 v130, s[10:11]
	v_mfma_f32_16x16x32_bf16 v[78:81], v[162:165], v[170:173], v[78:81]
	v_mfma_f32_16x16x32_bf16 v[70:73], v[162:165], v[174:177], v[70:73]
	s_add_u32 m0, s13, 0x800
	v_mfma_f32_16x16x32_bf16 v[62:65], v[162:165], v[178:181], v[62:65]
	global_load_lds_dwordx4 v132, s[10:11]
	v_mfma_f32_16x16x32_bf16 v[54:57], v[162:165], v[200:203], v[54:57]
	v_mfma_f32_16x16x32_bf16 v[46:49], v[166:169], v[170:173], v[46:49]
	s_add_u32 m0, s13, 0xc00
	v_mfma_f32_16x16x32_bf16 v[38:41], v[166:169], v[174:177], v[38:41]
	global_load_lds_dwordx4 v136, s[10:11]
	v_mfma_f32_16x16x32_bf16 v[30:33], v[166:169], v[178:181], v[30:33]
	v_mfma_f32_16x16x32_bf16 v[22:25], v[166:169], v[200:203], v[22:25]
	s_waitcnt lgkmcnt(0)
	v_mfma_f32_16x16x32_bf16 v[106:109], v[154:157], v[204:207], v[106:109]
	v_mfma_f32_16x16x32_bf16 v[98:101], v[154:157], v[208:211], v[98:101]
	s_mov_b32 m0, s68
	v_mfma_f32_16x16x32_bf16 v[90:93], v[154:157], v[212:215], v[90:93]
	global_load_lds_dwordx4 v138, s[64:65]
	v_mfma_f32_16x16x32_bf16 v[82:85], v[154:157], v[216:219], v[82:85]
	v_mfma_f32_16x16x32_bf16 v[74:77], v[158:161], v[204:207], v[74:77]
	v_mfma_f32_16x16x32_bf16 v[66:69], v[158:161], v[208:211], v[66:69]
	v_mfma_f32_16x16x32_bf16 v[58:61], v[158:161], v[212:215], v[58:61]
	v_mfma_f32_16x16x32_bf16 v[50:53], v[158:161], v[216:219], v[50:53]
	s_add_u32 m0, s68, 0x400
	v_mfma_f32_16x16x32_bf16 v[42:45], v[162:165], v[204:207], v[42:45]
	global_load_lds_dwordx4 v140, s[64:65]
	v_mfma_f32_16x16x32_bf16 v[34:37], v[162:165], v[208:211], v[34:37]
	v_mfma_f32_16x16x32_bf16 v[26:29], v[162:165], v[212:215], v[26:29]
	v_mfma_f32_16x16x32_bf16 v[18:21], v[162:165], v[216:219], v[18:21]
	v_mfma_f32_16x16x32_bf16 v[14:17], v[166:169], v[204:207], v[14:17]
	v_mfma_f32_16x16x32_bf16 v[10:13], v[166:169], v[208:211], v[10:13]
	v_mfma_f32_16x16x32_bf16 v[6:9], v[166:169], v[212:215], v[6:9]
	v_mfma_f32_16x16x32_bf16 v[2:5], v[166:169], v[216:219], v[2:5]
	s_add_i32 s10, s7, 0x6000
	s_cmpk_lg_u32 s7, 0xc000
	s_cselect_b32 s7, s10, 0
	s_addk_i32 s100, 0x400
	s_add_u32 s50, s50, s60
	s_addc_u32 s51, s51, 0
	s_cmpk_lg_i32 s100, 0x7800
	s_cbranch_scc1 .LBB0_246
	s_waitcnt vmcnt(6)
	s_barrier
	v_add_u32_e32 v0, s7, v150
	v_add_u32_e32 v140, s7, v149
	ds_read_b128 v[130:133], v0 offset:0
	ds_read_b128 v[136:139], v0 offset:0x400
	ds_read_b128 v[154:157], v0 offset:0x800
	ds_read_b128 v[158:161], v0 offset:0xc00
	ds_read_b128 v[162:165], v140 offset:0
	ds_read_b128 v[166:169], v140 offset:0x400
	ds_read_b128 v[170:173], v140 offset:0x800
	ds_read_b128 v[174:177], v140 offset:0xc00
	ds_read_b128 v[178:181], v140 offset:0x1000
	ds_read_b128 v[200:203], v140 offset:0x1400
	ds_read_b128 v[204:207], v140 offset:0x1800
	ds_read_b128 v[208:211], v140 offset:0x1c00
	s_lshl_b32 s49, s4, 8
	s_waitcnt lgkmcnt(4)
	s_nop 0
	v_mfma_f32_16x16x32_bf16 v[126:129], v[130:133], v[162:165], v[126:129]
	v_mfma_f32_16x16x32_bf16 v[118:121], v[130:133], v[170:173], v[118:121]
	v_mfma_f32_16x16x32_bf16 v[114:117], v[130:133], v[174:177], v[114:117]
	v_mfma_f32_16x16x32_bf16 v[110:113], v[136:139], v[162:165], v[110:113]
	v_mfma_f32_16x16x32_bf16 v[102:105], v[136:139], v[166:169], v[102:105]
	v_mfma_f32_16x16x32_bf16 v[94:97], v[136:139], v[170:173], v[94:97]
	v_mfma_f32_16x16x32_bf16 v[86:89], v[136:139], v[174:177], v[86:89]
	v_mfma_f32_16x16x32_bf16 v[70:73], v[154:157], v[166:169], v[70:73]
	v_mfma_f32_16x16x32_bf16 v[62:65], v[154:157], v[170:173], v[62:65]
	v_mfma_f32_16x16x32_bf16 v[54:57], v[154:157], v[174:177], v[54:57]
	v_mfma_f32_16x16x32_bf16 v[46:49], v[158:161], v[162:165], v[46:49]
	v_mfma_f32_16x16x32_bf16 v[38:41], v[158:161], v[166:169], v[38:41]
	v_mfma_f32_16x16x32_bf16 v[30:33], v[158:161], v[170:173], v[30:33]
	v_mfma_f32_16x16x32_bf16 v[22:25], v[158:161], v[174:177], v[22:25]
	v_mfma_f32_16x16x32_bf16 v[212:215], v[130:133], v[166:169], v[122:125]
	v_mfma_f32_16x16x32_bf16 v[216:219], v[154:157], v[162:165], v[78:81]
	s_waitcnt lgkmcnt(0)
	s_nop 0
	v_mfma_f32_16x16x32_bf16 v[174:177], v[136:139], v[178:181], v[74:77]
	v_mfma_f32_16x16x32_bf16 v[220:223], v[136:139], v[200:203], v[66:69]
	v_mfma_f32_16x16x32_bf16 v[224:227], v[136:139], v[204:207], v[58:61]
	v_mfma_f32_16x16x32_bf16 v[50:53], v[136:139], v[208:211], v[50:53]
	v_mfma_f32_16x16x32_bf16 v[136:139], v[154:157], v[178:181], v[42:45]
	v_mfma_f32_16x16x32_bf16 v[34:37], v[154:157], v[200:203], v[34:37]
	v_mfma_f32_16x16x32_bf16 v[6:9], v[158:161], v[204:207], v[6:9]
	v_mfma_f32_16x16x32_bf16 v[162:165], v[130:133], v[178:181], v[106:109]
	v_mfma_f32_16x16x32_bf16 v[166:169], v[130:133], v[200:203], v[98:101]
	v_mfma_f32_16x16x32_bf16 v[170:173], v[130:133], v[204:207], v[90:93]
	v_mfma_f32_16x16x32_bf16 v[130:133], v[130:133], v[208:211], v[82:85]
	v_mfma_f32_16x16x32_bf16 v[228:231], v[154:157], v[204:207], v[26:29]
	v_mfma_f32_16x16x32_bf16 v[154:157], v[154:157], v[208:211], v[18:21]
	v_mfma_f32_16x16x32_bf16 v[178:181], v[158:161], v[178:181], v[14:17]
	v_mfma_f32_16x16x32_bf16 v[200:203], v[158:161], v[200:203], v[10:13]
	v_mfma_f32_16x16x32_bf16 v[158:161], v[158:161], v[208:211], v[2:5]
	s_waitcnt vmcnt(0)
	s_barrier
	ds_read_b128 v[2:5], v151 offset:0
	ds_read_b128 v[14:17], v151 offset:0x400
	ds_read_b128 v[204:207], v151 offset:0x800
	ds_read_b128 v[208:211], v151 offset:0xc00
	ds_read_b128 v[10:13], v152 offset:0
	ds_read_b128 v[18:21], v152 offset:0x400
	ds_read_b128 v[26:29], v152 offset:0x800
	ds_read_b128 v[42:45], v152 offset:0xc00
	ds_read_b128 v[232:235], v152 offset:0x1000
	ds_read_b128 v[236:239], v152 offset:0x1400
	ds_read_b128 v[240:243], v152 offset:0x1800
	ds_read_b128 v[244:247], v152 offset:0x1c00
	s_nop 0
	s_waitcnt lgkmcnt(4)
	s_nop 0
	v_mfma_f32_16x16x32_bf16 v[122:125], v[2:5], v[10:13], v[126:129]
	v_mfma_f32_16x16x32_bf16 v[106:109], v[2:5], v[18:21], v[212:215]
	v_mfma_f32_16x16x32_bf16 v[90:93], v[2:5], v[26:29], v[118:121]
	v_mfma_f32_16x16x32_bf16 v[74:77], v[2:5], v[42:45], v[114:117]
	v_mfma_f32_16x16x32_bf16 v[126:129], v[14:17], v[10:13], v[110:113]
	v_mfma_f32_16x16x32_bf16 v[110:113], v[14:17], v[18:21], v[102:105]
	v_mfma_f32_16x16x32_bf16 v[94:97], v[14:17], v[26:29], v[94:97]
	v_mfma_f32_16x16x32_bf16 v[78:81], v[14:17], v[42:45], v[86:89]
	v_mfma_f32_16x16x32_bf16 v[114:117], v[204:207], v[10:13], v[216:219]
	v_mfma_f32_16x16x32_bf16 v[98:101], v[204:207], v[18:21], v[70:73]
	v_mfma_f32_16x16x32_bf16 v[82:85], v[204:207], v[26:29], v[62:65]
	v_mfma_f32_16x16x32_bf16 v[66:69], v[204:207], v[42:45], v[54:57]
	v_mfma_f32_16x16x32_bf16 v[118:121], v[208:211], v[10:13], v[46:49]
	v_mfma_f32_16x16x32_bf16 v[102:105], v[208:211], v[18:21], v[38:41]
	v_mfma_f32_16x16x32_bf16 v[86:89], v[208:211], v[26:29], v[30:33]
	v_mfma_f32_16x16x32_bf16 v[70:73], v[208:211], v[42:45], v[22:25]
	s_waitcnt lgkmcnt(0)
	s_nop 0
	v_mfma_f32_16x16x32_bf16 v[58:61], v[2:5], v[232:235], v[162:165]
	v_mfma_f32_16x16x32_bf16 v[42:45], v[2:5], v[236:239], v[166:169]
	v_mfma_f32_16x16x32_bf16 v[26:29], v[2:5], v[240:243], v[170:173]
	v_mfma_f32_16x16x32_bf16 v[10:13], v[2:5], v[244:247], v[130:133]
	v_mfma_f32_16x16x32_bf16 v[62:65], v[14:17], v[232:235], v[174:177]
	v_mfma_f32_16x16x32_bf16 v[46:49], v[14:17], v[236:239], v[220:223]
	v_mfma_f32_16x16x32_bf16 v[30:33], v[14:17], v[240:243], v[224:227]
	v_mfma_f32_16x16x32_bf16 v[14:17], v[14:17], v[244:247], v[50:53]
	v_mfma_f32_16x16x32_bf16 v[50:53], v[204:207], v[232:235], v[136:139]
	v_mfma_f32_16x16x32_bf16 v[34:37], v[204:207], v[236:239], v[34:37]
	v_mfma_f32_16x16x32_bf16 v[18:21], v[204:207], v[240:243], v[228:231]
	v_mfma_f32_16x16x32_bf16 v[2:5], v[204:207], v[244:247], v[154:157]
	v_mfma_f32_16x16x32_bf16 v[54:57], v[208:211], v[232:235], v[178:181]
	v_mfma_f32_16x16x32_bf16 v[38:41], v[208:211], v[236:239], v[200:203]
	v_mfma_f32_16x16x32_bf16 v[22:25], v[208:211], v[240:243], v[6:9]
	v_mfma_f32_16x16x32_bf16 v[6:9], v[208:211], v[244:247], v[158:161]
	v_mov_b32_e32 v136, v134
	s_mov_b64 s[50:51], -1
	s_and_b64 vcc, exec, s[22:23]
	s_barrier
	s_cbranch_vccz .LBB0_264
	s_and_b64 vcc, exec, s[0:1]
	s_cbranch_vccz .LBB0_250
	v_lshrrev_b32_e32 v0, 6, v136
	v_mul_lo_u32 v137, v0, s14
	v_and_b32_e32 v130, 15, v136
	v_and_or_b32 v0, v136, 48, v137
	s_movk_i32 s4, 0x90
	v_mad_u32_u24 v0, v130, s4, v0
	v_cvt_pk_bf16_f32 v130, v122, v123
	v_cvt_pk_bf16_f32 v131, v124, v125
	v_cvt_pk_bf16_f32 v132, v126, v127
	v_cvt_pk_bf16_f32 v133, v128, v129
	s_waitcnt vmcnt(0)
	ds_write_b128 v0, v[130:133]
	v_cvt_pk_bf16_f32 v130, v114, v115
	v_cvt_pk_bf16_f32 v131, v116, v117
	v_cvt_pk_bf16_f32 v132, v118, v119
	v_cvt_pk_bf16_f32 v133, v120, v121
	ds_write_b128 v0, v[130:133] offset:64
	v_cvt_pk_bf16_f32 v130, v106, v107
	v_cvt_pk_bf16_f32 v131, v108, v109
	v_cvt_pk_bf16_f32 v132, v110, v111
	v_cvt_pk_bf16_f32 v133, v112, v113
	ds_write_b128 v0, v[130:133] offset:2304
	v_cvt_pk_bf16_f32 v130, v98, v99
	v_cvt_pk_bf16_f32 v131, v100, v101
	v_cvt_pk_bf16_f32 v132, v102, v103
	v_cvt_pk_bf16_f32 v133, v104, v105
	ds_write_b128 v0, v[130:133] offset:2368
	v_cvt_pk_bf16_f32 v130, v90, v91
	v_cvt_pk_bf16_f32 v131, v92, v93
	v_cvt_pk_bf16_f32 v132, v94, v95
	v_cvt_pk_bf16_f32 v133, v96, v97
	ds_write_b128 v0, v[130:133] offset:4608
	v_cvt_pk_bf16_f32 v130, v82, v83
	v_cvt_pk_bf16_f32 v131, v84, v85
	v_cvt_pk_bf16_f32 v132, v86, v87
	v_cvt_pk_bf16_f32 v133, v88, v89
	ds_write_b128 v0, v[130:133] offset:4672
	v_cvt_pk_bf16_f32 v130, v74, v75
	v_cvt_pk_bf16_f32 v131, v76, v77
	v_cvt_pk_bf16_f32 v132, v78, v79
	v_cvt_pk_bf16_f32 v133, v80, v81
	ds_write_b128 v0, v[130:133] offset:6912
	v_cvt_pk_bf16_f32 v130, v66, v67
	v_cvt_pk_bf16_f32 v131, v68, v69
	v_cvt_pk_bf16_f32 v132, v70, v71
	v_cvt_pk_bf16_f32 v133, v72, v73
	ds_write_b128 v0, v[130:133] offset:6976
	v_cvt_pk_bf16_f32 v130, v58, v59
	v_cvt_pk_bf16_f32 v131, v60, v61
	v_cvt_pk_bf16_f32 v132, v62, v63
	v_cvt_pk_bf16_f32 v133, v64, v65
	ds_write_b128 v0, v[130:133] offset:9216
	v_cvt_pk_bf16_f32 v130, v50, v51
	v_cvt_pk_bf16_f32 v131, v52, v53
	v_cvt_pk_bf16_f32 v132, v54, v55
	v_cvt_pk_bf16_f32 v133, v56, v57
	ds_write_b128 v0, v[130:133] offset:9280
	v_cvt_pk_bf16_f32 v130, v42, v43
	v_cvt_pk_bf16_f32 v131, v44, v45
	v_cvt_pk_bf16_f32 v132, v46, v47
	v_cvt_pk_bf16_f32 v133, v48, v49
	ds_write_b128 v0, v[130:133] offset:11520
	v_cvt_pk_bf16_f32 v130, v34, v35
	v_cvt_pk_bf16_f32 v131, v36, v37
	v_cvt_pk_bf16_f32 v132, v38, v39
	v_cvt_pk_bf16_f32 v133, v40, v41
	ds_write_b128 v0, v[130:133] offset:11584
	v_cvt_pk_bf16_f32 v130, v26, v27
	v_cvt_pk_bf16_f32 v131, v28, v29
	v_cvt_pk_bf16_f32 v132, v30, v31
	v_cvt_pk_bf16_f32 v133, v32, v33
	ds_write_b128 v0, v[130:133] offset:13824
	v_cvt_pk_bf16_f32 v130, v18, v19
	v_cvt_pk_bf16_f32 v131, v20, v21
	v_cvt_pk_bf16_f32 v132, v22, v23
	v_cvt_pk_bf16_f32 v133, v24, v25
	ds_write_b128 v0, v[130:133] offset:13888
	v_cvt_pk_bf16_f32 v130, v10, v11
	v_cvt_pk_bf16_f32 v131, v12, v13
	v_cvt_pk_bf16_f32 v132, v14, v15
	v_cvt_pk_bf16_f32 v133, v16, v17
	ds_write_b128 v0, v[130:133] offset:16128
	v_cvt_pk_bf16_f32 v130, v2, v3
	v_cvt_pk_bf16_f32 v131, v4, v5
	v_cvt_pk_bf16_f32 v132, v6, v7
	v_cvt_pk_bf16_f32 v133, v8, v9
	ds_write_b128 v0, v[130:133] offset:16192
	v_and_b32_e32 v0, 0xffffff80, v136
	v_add_u32_e32 v130, s48, v0
	v_ashrrev_i32_e32 v131, 31, v130
	v_lshlrev_b64 v[130:131], 11, v[130:131]
	v_lshl_add_u64 v[130:131], s[38:39], 0, v[130:131]
	v_and_b32_e32 v0, 64, v136
	v_lshl_add_u64 v[130:131], s[46:47], 1, v[130:131]
	v_lshlrev_b32_e32 v0, 1, v0
	v_lshl_add_u64 v[138:139], v[130:131], 0, v[0:1]
	v_lshlrev_b32_e32 v0, 4, v136
	v_and_b32_e32 v0, 0x70, v0
	v_bfe_u32 v140, v136, 3, 3
	v_or_b32_e32 v130, v137, v0
	s_waitcnt lgkmcnt(0)
	v_mad_u32_u24 v137, v140, s4, v130
	ds_read_b128 v[66:69], v137
	ds_read_b128 v[70:73], v137 offset:1152
	ds_read_b128 v[74:77], v137 offset:2304
	ds_read_b128 v[78:81], v137 offset:3456
	ds_read_b128 v[82:85], v137 offset:4608
	ds_read_b128 v[86:89], v137 offset:5760
	ds_read_b128 v[90:93], v137 offset:6912
	ds_read_b128 v[94:97], v137 offset:8064
	ds_read_b128 v[98:101], v137 offset:9216
	ds_read_b128 v[102:105], v137 offset:10368
	ds_read_b128 v[106:109], v137 offset:11520
	ds_read_b128 v[110:113], v137 offset:12672
	ds_read_b128 v[114:117], v137 offset:13824
	ds_read_b128 v[118:121], v137 offset:14976
	ds_read_b128 v[122:125], v137 offset:16128
	ds_read_b128 v[126:129], v137 offset:17280
	v_lshl_add_u64 v[138:139], v[138:139], 0, v[0:1]
	v_lshlrev_b32_e32 v0, 11, v140
	v_lshl_add_u64 v[140:141], v[138:139], 0, v[0:1]
	s_mov_b64 s[50:51], 0
	s_waitcnt lgkmcnt(15)
	global_store_dwordx4 v[140:141], v[66:69], off
	v_or_b32_e32 v140, 0x4000, v0
	v_mov_b32_e32 v141, v1
	v_lshl_add_u64 v[140:141], v[138:139], 0, v[140:141]
	s_waitcnt lgkmcnt(14)
	global_store_dwordx4 v[140:141], v[70:73], off
	v_or_b32_e32 v140, 0x8000, v0
	v_mov_b32_e32 v141, v1
	v_lshl_add_u64 v[140:141], v[138:139], 0, v[140:141]
	s_waitcnt lgkmcnt(13)
	global_store_dwordx4 v[140:141], v[74:77], off
	v_or_b32_e32 v140, 0xc000, v0
	v_mov_b32_e32 v141, v1
	v_lshl_add_u64 v[140:141], v[138:139], 0, v[140:141]
	s_waitcnt lgkmcnt(12)
	global_store_dwordx4 v[140:141], v[78:81], off
	v_or_b32_e32 v140, 0x10000, v0
	v_mov_b32_e32 v141, v1
	v_lshl_add_u64 v[140:141], v[138:139], 0, v[140:141]
	s_waitcnt lgkmcnt(11)
	global_store_dwordx4 v[140:141], v[82:85], off
	v_or_b32_e32 v140, 0x14000, v0
	v_mov_b32_e32 v141, v1
	v_lshl_add_u64 v[140:141], v[138:139], 0, v[140:141]
	s_waitcnt lgkmcnt(10)
	global_store_dwordx4 v[140:141], v[86:89], off
	v_or_b32_e32 v140, 0x18000, v0
	v_mov_b32_e32 v141, v1
	v_lshl_add_u64 v[140:141], v[138:139], 0, v[140:141]
	s_waitcnt lgkmcnt(9)
	global_store_dwordx4 v[140:141], v[90:93], off
	v_or_b32_e32 v140, 0x1c000, v0
	v_mov_b32_e32 v141, v1
	v_lshl_add_u64 v[140:141], v[138:139], 0, v[140:141]
	s_waitcnt lgkmcnt(8)
	global_store_dwordx4 v[140:141], v[94:97], off
	v_or_b32_e32 v140, 0x20000, v0
	v_mov_b32_e32 v141, v1
	v_lshl_add_u64 v[140:141], v[138:139], 0, v[140:141]
	s_waitcnt lgkmcnt(7)
	global_store_dwordx4 v[140:141], v[98:101], off
	v_or_b32_e32 v140, 0x24000, v0
	v_mov_b32_e32 v141, v1
	v_lshl_add_u64 v[140:141], v[138:139], 0, v[140:141]
	s_waitcnt lgkmcnt(6)
	global_store_dwordx4 v[140:141], v[102:105], off
	v_or_b32_e32 v140, 0x28000, v0
	v_mov_b32_e32 v141, v1
	v_lshl_add_u64 v[140:141], v[138:139], 0, v[140:141]
	s_waitcnt lgkmcnt(5)
	global_store_dwordx4 v[140:141], v[106:109], off
	v_or_b32_e32 v140, 0x2c000, v0
	v_mov_b32_e32 v141, v1
	v_lshl_add_u64 v[140:141], v[138:139], 0, v[140:141]
	s_waitcnt lgkmcnt(4)
	global_store_dwordx4 v[140:141], v[110:113], off
	v_or_b32_e32 v140, 0x30000, v0
	v_mov_b32_e32 v141, v1
	v_lshl_add_u64 v[140:141], v[138:139], 0, v[140:141]
	s_waitcnt lgkmcnt(3)
	global_store_dwordx4 v[140:141], v[114:117], off
	v_or_b32_e32 v140, 0x34000, v0
	v_mov_b32_e32 v141, v1
	v_lshl_add_u64 v[140:141], v[138:139], 0, v[140:141]
	s_waitcnt lgkmcnt(2)
	global_store_dwordx4 v[140:141], v[118:121], off
	v_or_b32_e32 v140, 0x38000, v0
	v_mov_b32_e32 v141, v1
	v_lshl_add_u64 v[140:141], v[138:139], 0, v[140:141]
	v_or_b32_e32 v0, 0x3c000, v0
	s_waitcnt lgkmcnt(1)
	global_store_dwordx4 v[140:141], v[122:125], off
	v_lshl_add_u64 v[138:139], v[138:139], 0, v[0:1]
	s_waitcnt lgkmcnt(0)
	global_store_dwordx4 v[138:139], v[126:129], off
	s_waitcnt lgkmcnt(0)
	s_barrier
